# baseline (speedup 1.0000x reference)
; __device__ __forceinline__ unsigned cvt_pk_bf16(float lo, float hi) { unsigned r; asm volatile("v_cvt_pk_bf16_f32 %0, %1, %2" : "=v"(r) : "v"(lo), "v"(hi)); return r; }
; __device__ __forceinline__ float log2_gamma(int h) { return log2f(1.0f - exp2f(-5.0f - (float)h)); }
; __device__ __forceinline__ void ret_stepB(const Params& p) {
;     ...
;     for (int e4 = blockIdx.x * NTHREADS + tid_o; e4 < 32 * 4096; e4 += gridDim.x * NTHREADS) {
;         const int bh = e4 >> 12, off = (e4 & 4095) * 4, h = bh & 7;
;         const float decay = exp2f(log2_gamma(h) * 128.0f);
;         f32x4 R = {0, 0, 0, 0};
; #pragma unroll 8
;         for (int n = 0; n < 64; ++n) {
;             const size_t o = (size_t)(bh * 64 + n) * 16384 + off;
;             const f32x4 s = *(const f32x4*)(S + o);
;             u32x2 w; w.x = cvt_pk_bf16(R[0], R[1]); w.y = cvt_pk_bf16(R[2], R[3]);
;             *(u32x2*)(RT + o) = w;
;             R = R * decay + s;
;         }
.LBB0_278:
	s_waitcnt lgkmcnt(0)
	v_lshl_add_u64 v[26:27], s[14:15], 0, v[6:7]
	v_add_co_u32_e32 v26, vcc, 0x6730000, v26
	s_nop 1
	v_addc_co_u32_e32 v27, vcc, 0, v27, vcc
	v_lshl_add_u64 v[28:29], s[14:15], 0, v[4:5]
	v_add_co_u32_e32 v28, vcc, 0x31730000, v28
	s_nop 1
	v_addc_co_u32_e32 v29, vcc, 0, v29, vcc
	s_mov_b32 s98, 0x10000
	s_mov_b32 s99, 0
	s_mov_b32 s100, 0x8000
	s_mov_b32 s101, 0
	global_load_dwordx4 v[40:43], v[26:27], off
	v_lshl_add_u64 v[26:27], v[26:27], 0, s[98:99]
	global_load_dwordx4 v[44:47], v[26:27], off
	v_lshl_add_u64 v[26:27], v[26:27], 0, s[98:99]
	global_load_dwordx4 v[48:51], v[26:27], off
	v_lshl_add_u64 v[26:27], v[26:27], 0, s[98:99]
	global_load_dwordx4 v[52:55], v[26:27], off
	v_lshl_add_u64 v[26:27], v[26:27], 0, s[98:99]
	global_load_dwordx4 v[56:59], v[26:27], off
	v_lshl_add_u64 v[26:27], v[26:27], 0, s[98:99]
	global_load_dwordx4 v[60:63], v[26:27], off
	v_lshl_add_u64 v[26:27], v[26:27], 0, s[98:99]
	global_load_dwordx4 v[64:67], v[26:27], off
	v_lshl_add_u64 v[26:27], v[26:27], 0, s[98:99]
	global_load_dwordx4 v[68:71], v[26:27], off
	v_lshl_add_u64 v[26:27], v[26:27], 0, s[98:99]
	global_load_dwordx4 v[72:75], v[26:27], off
	v_lshl_add_u64 v[26:27], v[26:27], 0, s[98:99]
	global_load_dwordx4 v[76:79], v[26:27], off
	v_lshl_add_u64 v[26:27], v[26:27], 0, s[98:99]
	global_load_dwordx4 v[80:83], v[26:27], off
	v_lshl_add_u64 v[26:27], v[26:27], 0, s[98:99]
	global_load_dwordx4 v[84:87], v[26:27], off
	v_lshl_add_u64 v[26:27], v[26:27], 0, s[98:99]
	global_load_dwordx4 v[88:91], v[26:27], off
	v_lshl_add_u64 v[26:27], v[26:27], 0, s[98:99]
	global_load_dwordx4 v[92:95], v[26:27], off
	v_lshl_add_u64 v[26:27], v[26:27], 0, s[98:99]
	global_load_dwordx4 v[96:99], v[26:27], off
	v_lshl_add_u64 v[26:27], v[26:27], 0, s[98:99]
	global_load_dwordx4 v[100:103], v[26:27], off
	v_cvt_pk_bf16_f32 v38, v8, v9
	v_cvt_pk_bf16_f32 v39, v10, v11
	global_store_dwordx2 v[28:29], v[38:39], off
	v_lshl_add_u64 v[28:29], v[28:29], 0, s[100:101]
	s_waitcnt vmcnt(16)
	v_pk_fma_f32 v[8:9], v[0:1], v[8:9], v[40:41]
	v_pk_fma_f32 v[10:11], v[2:3], v[10:11], v[42:43]
	v_cvt_pk_bf16_f32 v38, v8, v9
	v_cvt_pk_bf16_f32 v39, v10, v11
	global_store_dwordx2 v[28:29], v[38:39], off
	v_lshl_add_u64 v[28:29], v[28:29], 0, s[100:101]
	s_waitcnt vmcnt(16)
	v_pk_fma_f32 v[8:9], v[0:1], v[8:9], v[44:45]
	v_pk_fma_f32 v[10:11], v[2:3], v[10:11], v[46:47]
	v_cvt_pk_bf16_f32 v38, v8, v9
	v_cvt_pk_bf16_f32 v39, v10, v11
	global_store_dwordx2 v[28:29], v[38:39], off
	v_lshl_add_u64 v[28:29], v[28:29], 0, s[100:101]
	s_waitcnt vmcnt(16)
	v_pk_fma_f32 v[8:9], v[0:1], v[8:9], v[48:49]
	v_pk_fma_f32 v[10:11], v[2:3], v[10:11], v[50:51]
	v_cvt_pk_bf16_f32 v38, v8, v9
	v_cvt_pk_bf16_f32 v39, v10, v11
	global_store_dwordx2 v[28:29], v[38:39], off
	v_lshl_add_u64 v[28:29], v[28:29], 0, s[100:101]
	s_waitcnt vmcnt(16)
	v_pk_fma_f32 v[8:9], v[0:1], v[8:9], v[52:53]
	v_pk_fma_f32 v[10:11], v[2:3], v[10:11], v[54:55]
	v_cvt_pk_bf16_f32 v38, v8, v9
	v_cvt_pk_bf16_f32 v39, v10, v11
	global_store_dwordx2 v[28:29], v[38:39], off
	v_lshl_add_u64 v[28:29], v[28:29], 0, s[100:101]
	s_waitcnt vmcnt(16)
	v_pk_fma_f32 v[8:9], v[0:1], v[8:9], v[56:57]
	v_pk_fma_f32 v[10:11], v[2:3], v[10:11], v[58:59]
	v_cvt_pk_bf16_f32 v38, v8, v9
	v_cvt_pk_bf16_f32 v39, v10, v11
	global_store_dwordx2 v[28:29], v[38:39], off
	v_lshl_add_u64 v[28:29], v[28:29], 0, s[100:101]
	s_waitcnt vmcnt(16)
	v_pk_fma_f32 v[8:9], v[0:1], v[8:9], v[60:61]
	v_pk_fma_f32 v[10:11], v[2:3], v[10:11], v[62:63]
	v_cvt_pk_bf16_f32 v38, v8, v9
	v_cvt_pk_bf16_f32 v39, v10, v11
	global_store_dwordx2 v[28:29], v[38:39], off
	v_lshl_add_u64 v[28:29], v[28:29], 0, s[100:101]
	s_waitcnt vmcnt(16)
	v_pk_fma_f32 v[8:9], v[0:1], v[8:9], v[64:65]
	v_pk_fma_f32 v[10:11], v[2:3], v[10:11], v[66:67]
	v_cvt_pk_bf16_f32 v38, v8, v9
	v_cvt_pk_bf16_f32 v39, v10, v11
	global_store_dwordx2 v[28:29], v[38:39], off
	v_lshl_add_u64 v[28:29], v[28:29], 0, s[100:101]
	s_waitcnt vmcnt(16)
	v_pk_fma_f32 v[8:9], v[0:1], v[8:9], v[68:69]
	v_pk_fma_f32 v[10:11], v[2:3], v[10:11], v[70:71]
	v_cvt_pk_bf16_f32 v38, v8, v9
	v_cvt_pk_bf16_f32 v39, v10, v11
	global_store_dwordx2 v[28:29], v[38:39], off
	v_lshl_add_u64 v[28:29], v[28:29], 0, s[100:101]
	s_waitcnt vmcnt(16)
	v_pk_fma_f32 v[8:9], v[0:1], v[8:9], v[72:73]
	v_pk_fma_f32 v[10:11], v[2:3], v[10:11], v[74:75]
	v_cvt_pk_bf16_f32 v38, v8, v9
	v_cvt_pk_bf16_f32 v39, v10, v11
	global_store_dwordx2 v[28:29], v[38:39], off
	v_lshl_add_u64 v[28:29], v[28:29], 0, s[100:101]
	s_waitcnt vmcnt(16)
	v_pk_fma_f32 v[8:9], v[0:1], v[8:9], v[76:77]
	v_pk_fma_f32 v[10:11], v[2:3], v[10:11], v[78:79]
	v_cvt_pk_bf16_f32 v38, v8, v9
	v_cvt_pk_bf16_f32 v39, v10, v11
	global_store_dwordx2 v[28:29], v[38:39], off
	v_lshl_add_u64 v[28:29], v[28:29], 0, s[100:101]
	s_waitcnt vmcnt(16)
	v_pk_fma_f32 v[8:9], v[0:1], v[8:9], v[80:81]
	v_pk_fma_f32 v[10:11], v[2:3], v[10:11], v[82:83]
	v_cvt_pk_bf16_f32 v38, v8, v9
	v_cvt_pk_bf16_f32 v39, v10, v11
	global_store_dwordx2 v[28:29], v[38:39], off
	v_lshl_add_u64 v[28:29], v[28:29], 0, s[100:101]
	s_waitcnt vmcnt(16)
	v_pk_fma_f32 v[8:9], v[0:1], v[8:9], v[84:85]
	v_pk_fma_f32 v[10:11], v[2:3], v[10:11], v[86:87]
	v_cvt_pk_bf16_f32 v38, v8, v9
	v_cvt_pk_bf16_f32 v39, v10, v11
	global_store_dwordx2 v[28:29], v[38:39], off
	v_lshl_add_u64 v[28:29], v[28:29], 0, s[100:101]
	s_waitcnt vmcnt(16)
	v_pk_fma_f32 v[8:9], v[0:1], v[8:9], v[88:89]
	v_pk_fma_f32 v[10:11], v[2:3], v[10:11], v[90:91]
	v_cvt_pk_bf16_f32 v38, v8, v9
	v_cvt_pk_bf16_f32 v39, v10, v11
	global_store_dwordx2 v[28:29], v[38:39], off
	v_lshl_add_u64 v[28:29], v[28:29], 0, s[100:101]
	s_waitcnt vmcnt(16)
	v_pk_fma_f32 v[8:9], v[0:1], v[8:9], v[92:93]
	v_pk_fma_f32 v[10:11], v[2:3], v[10:11], v[94:95]
	v_cvt_pk_bf16_f32 v38, v8, v9
	v_cvt_pk_bf16_f32 v39, v10, v11
	global_store_dwordx2 v[28:29], v[38:39], off
	v_lshl_add_u64 v[28:29], v[28:29], 0, s[100:101]
	s_waitcnt vmcnt(16)
	v_pk_fma_f32 v[8:9], v[0:1], v[8:9], v[96:97]
	v_pk_fma_f32 v[10:11], v[2:3], v[10:11], v[98:99]
	v_cvt_pk_bf16_f32 v38, v8, v9
	v_cvt_pk_bf16_f32 v39, v10, v11
	global_store_dwordx2 v[28:29], v[38:39], off
	v_lshl_add_u64 v[28:29], v[28:29], 0, s[100:101]
	s_waitcnt vmcnt(16)
	v_pk_fma_f32 v[8:9], v[0:1], v[8:9], v[100:101]
	v_pk_fma_f32 v[10:11], v[2:3], v[10:11], v[102:103]
	v_lshl_add_u64 v[4:5], v[4:5], 0, s[8:9]
	v_lshl_add_u64 v[4:5], v[4:5], 0, s[8:9]
	v_lshl_add_u64 v[6:7], v[6:7], 0, s[10:11]
	v_lshl_add_u64 v[6:7], v[6:7], 0, s[10:11]
	s_add_i32 s26, s26, -16
	s_cmp_eq_u32 s26, 0
	s_cbranch_scc0 .LBB0_278
	v_add_u32_e32 v15, s76, v15
	v_cmp_lt_i32_e32 vcc, s25, v15
	s_or_b64 s[16:17], vcc, s[16:17]
	v_add_u32_e32 v16, s66, v16
	s_andn2_b64 exec, exec, s[16:17]
	s_cbranch_execnz .LBB0_277
	s_branch .LBB0_274

; __global__ void __launch_bounds__(NTHREADS, 2) fwd_megakernel(ParamsT p_unused) {
	.amdhsa_kernel _Z14fwd_megakernel7ParamsT
		.amdhsa_group_segment_fixed_size 0
		.amdhsa_private_segment_fixed_size 0
		.amdhsa_kernarg_size 400
		.amdhsa_user_sgpr_count 2
		.amdhsa_user_sgpr_dispatch_ptr 0
		.amdhsa_user_sgpr_queue_ptr 0
		.amdhsa_user_sgpr_kernarg_segment_ptr 1
		.amdhsa_user_sgpr_dispatch_id 0
		.amdhsa_user_sgpr_kernarg_preload_length 0
		.amdhsa_user_sgpr_kernarg_preload_offset 0
		.amdhsa_user_sgpr_private_segment_size 0
		.amdhsa_uses_dynamic_stack 0
		.amdhsa_enable_private_segment 0
		.amdhsa_system_sgpr_workgroup_id_x 1
		.amdhsa_system_sgpr_workgroup_id_y 0
		.amdhsa_system_sgpr_workgroup_id_z 0
		.amdhsa_system_sgpr_workgroup_info 0
		.amdhsa_system_vgpr_workitem_id 2
		.amdhsa_next_free_vgpr 235
		.amdhsa_next_free_sgpr 102
		.amdhsa_accum_offset 236
		.amdhsa_reserve_vcc 1
		.amdhsa_float_round_mode_32 0
		.amdhsa_float_round_mode_16_64 0
		.amdhsa_float_denorm_mode_32 3
		.amdhsa_float_denorm_mode_16_64 3
		.amdhsa_dx10_clamp 1
		.amdhsa_ieee_mode 1
		.amdhsa_fp16_overflow 0
		.amdhsa_tg_split 0
		.amdhsa_exception_fp_ieee_invalid_op 0
		.amdhsa_exception_fp_denorm_src 0
		.amdhsa_exception_fp_ieee_div_zero 0
		.amdhsa_exception_fp_ieee_overflow 0
		.amdhsa_exception_fp_ieee_underflow 0
		.amdhsa_exception_fp_ieee_inexact 0
		.amdhsa_exception_int_div_zero 0
	.end_amdhsa_kernel

; __global__ void __launch_bounds__(NTHREADS, 2) fwd_megakernel(ParamsT p_unused) {
amdhsa.kernels:
  - .agpr_count:     0
    .args:
      - .offset:         0
        .size:           144
        .value_kind:     by_value
      - .offset:         144
        .size:           4
        .value_kind:     hidden_block_count_x
      - .offset:         148
        .size:           4
        .value_kind:     hidden_block_count_y
      - .offset:         152
        .size:           4
        .value_kind:     hidden_block_count_z
      - .offset:         156
        .size:           2
        .value_kind:     hidden_group_size_x
      - .offset:         158
        .size:           2
        .value_kind:     hidden_group_size_y
      - .offset:         160
        .size:           2
        .value_kind:     hidden_group_size_z
      - .offset:         162
        .size:           2
        .value_kind:     hidden_remainder_x
      - .offset:         164
        .size:           2
        .value_kind:     hidden_remainder_y
      - .offset:         166
        .size:           2
        .value_kind:     hidden_remainder_z
      - .offset:         184
        .size:           8
        .value_kind:     hidden_global_offset_x
      - .offset:         192
        .size:           8
        .value_kind:     hidden_global_offset_y
      - .offset:         200
        .size:           8
        .value_kind:     hidden_global_offset_z
      - .offset:         208
        .size:           2
        .value_kind:     hidden_grid_dims
      - .offset:         232
        .size:           8
        .value_kind:     hidden_multigrid_sync_arg
      - .offset:         264
        .size:           4
        .value_kind:     hidden_dynamic_lds_size
    .group_segment_fixed_size: 0
    .kernarg_segment_align: 8
    .kernarg_segment_size: 400
    .language:       OpenCL C
    .language_version:
      - 2
      - 0
    .max_flat_workgroup_size: 512
    .name:           _Z14fwd_megakernel7ParamsT
    .private_segment_fixed_size: 0
    .sgpr_count:     108
    .sgpr_spill_count: 5
    .symbol:         _Z14fwd_megakernel7ParamsT.kd
    .uniform_work_group_size: 1
    .uses_dynamic_stack: false
    .vgpr_count:     235
    .vgpr_spill_count: 0
    .wavefront_size: 64
